# back-edge rotation (7.11): K-loop counter/pointer SALU and next-iteration address setup moved ahead of the loop-back barrier in the 3 GEMM K-loops, on v25
# baseline (speedup 1.0000x reference)
.LBB0_576:
	s_ashr_i32 s25, s24, 31
	s_lshl_b64 s[0:1], s[24:25], 19
	s_add_u32 s28, s96, s0
	s_addc_u32 s29, s97, s1
	s_and_b64 s[0:1], s[36:37], exec
	s_cselect_b32 s25, s29, s47
	s_cselect_b32 s43, s28, s46
	s_ashr_i32 s27, s26, 31
	s_lshl_b64 s[0:1], s[26:27], 19
	v_readlane_b32 s30, v255, 7
	v_readlane_b32 s31, v255, 8
	s_add_u32 s30, s30, s0
	s_addc_u32 s31, s31, s1
	s_and_b64 s[0:1], s[36:37], exec
	s_cselect_b32 s27, s31, s45
	s_cselect_b32 s53, s30, s44
	s_add_u32 s72, s44, 0x100
	s_addc_u32 s73, s45, 0
	s_add_u32 s0, s46, 0x40080
	v_mov_b32_e32 v2, 0
	s_addc_u32 s1, s47, 0
	s_mov_b32 s74, -2
	v_mov_b32_e32 v3, v2
	v_mov_b64_e32 v[4:5], 0
	v_mov_b64_e32 v[6:7], 0
	v_mov_b64_e32 v[8:9], 0
	v_mov_b64_e32 v[10:11], 0
	v_mov_b64_e32 v[12:13], 0
	v_mov_b64_e32 v[14:15], 0
	v_mov_b64_e32 v[16:17], 0
	v_mov_b64_e32 v[18:19], 0
	v_mov_b64_e32 v[20:21], 0
	v_mov_b64_e32 v[22:23], 0
	v_mov_b64_e32 v[24:25], 0
	v_mov_b64_e32 v[26:27], 0
	v_mov_b64_e32 v[28:29], 0
	v_mov_b64_e32 v[30:31], 0
	v_mov_b64_e32 v[32:33], 0
	v_mov_b64_e32 v[34:35], 0
	v_mov_b64_e32 v[36:37], 0
	v_mov_b64_e32 v[38:39], 0
	v_mov_b64_e32 v[40:41], 0
	v_mov_b64_e32 v[42:43], 0
	v_mov_b64_e32 v[44:45], 0
	v_mov_b64_e32 v[46:47], 0
	v_mov_b64_e32 v[48:49], 0
	v_mov_b64_e32 v[50:51], 0
	v_mov_b64_e32 v[52:53], 0
	v_mov_b64_e32 v[54:55], 0
	v_mov_b64_e32 v[56:57], 0
	v_mov_b64_e32 v[58:59], 0
	v_mov_b64_e32 v[60:61], 0
	v_mov_b64_e32 v[62:63], 0
	v_mov_b64_e32 v[64:65], 0
	v_mov_b64_e32 v[66:67], 0
	v_mov_b64_e32 v[68:69], 0
	v_mov_b64_e32 v[78:79], 0
	v_mov_b64_e32 v[80:81], 0
	v_mov_b64_e32 v[98:99], 0
	v_mov_b64_e32 v[100:101], 0
	v_mov_b64_e32 v[110:111], 0
	v_mov_b64_e32 v[112:113], 0
	v_mov_b64_e32 v[114:115], 0
	v_mov_b64_e32 v[116:117], 0
	v_mov_b64_e32 v[118:119], 0
	v_mov_b64_e32 v[120:121], 0
	v_mov_b64_e32 v[122:123], 0
	v_mov_b64_e32 v[124:125], 0
	v_mov_b64_e32 v[126:127], 0
	v_mov_b64_e32 v[128:129], 0
	v_mov_b64_e32 v[130:131], 0
	v_mov_b64_e32 v[132:133], 0
	v_mov_b64_e32 v[134:135], 0
	v_mov_b64_e32 v[136:137], 0
	v_mov_b64_e32 v[138:139], 0
	v_mov_b64_e32 v[140:141], 0
	v_mov_b64_e32 v[142:143], 0
	v_mov_b64_e32 v[144:145], 0
	v_mov_b64_e32 v[146:147], 0
	v_mov_b64_e32 v[148:149], 0
	v_mov_b64_e32 v[150:151], 0
	v_mov_b64_e32 v[152:153], 0
	v_mov_b64_e32 v[154:155], 0
	v_mov_b64_e32 v[156:157], 0
	v_mov_b64_e32 v[158:159], 0
	v_mov_b64_e32 v[160:161], 0
	s_add_u32 s44, s0, 0xfffc0080
	s_addc_u32 s45, s1, -1
	s_add_i32 s75, 0, 0x10000
	s_cmp_eq_u32 s74, 12
	s_cselect_b32 s47, s25, s45
	s_cselect_b32 s46, s43, s44
	s_cselect_b32 s45, s27, s73
	s_cselect_b32 s44, s53, s72
	s_add_i32 s80, 0, 0x14000
	s_waitcnt lgkmcnt(0)
	v_add_u32_e32 v86, s75, v1
	v_add_u32_e32 v106, s80, v1
.LBB0_577:
	ds_read_b128 v[70:73], v86
	ds_read_b128 v[74:77], v86 offset:1024
	ds_read_b128 v[82:85], v86 offset:2048
	ds_read_b128 v[86:89], v86 offset:3072
	ds_read_b128 v[90:93], v106
	ds_read_b128 v[94:97], v106 offset:1024
	ds_read_b128 v[102:105], v106 offset:2048
	ds_read_b128 v[106:109], v106 offset:3072
	v_lshl_add_u64 v[220:221], s[0:1], 0, v[206:207]
	s_add_i32 m0, s41, 0xc000
	ds_read_b128 v[162:165], v187
	ds_read_b128 v[166:169], v187 offset:1024
	ds_read_b128 v[170:173], v187 offset:2048
	ds_read_b128 v[174:177], v187 offset:3072
	ds_read_b128 v[178:181], v187 offset:4096
	ds_read_b128 v[182:185], v187 offset:5120
	ds_read_b128 v[212:215], v187 offset:6144
	ds_read_b128 v[216:219], v187 offset:7168
	global_load_lds_dwordx4 v[220:221], off
	v_lshl_add_u64 v[220:221], s[0:1], 0, v[204:205]
	s_add_i32 m0, s41, 0xe000
	s_nop 0
	global_load_lds_dwordx4 v[220:221], off
	s_waitcnt vmcnt(8)
	s_waitcnt lgkmcnt(0)
	s_barrier
	s_setprio 1
	s_waitcnt lgkmcnt(0)
	v_mfma_f32_16x16x32_bf16 v[158:161], v[70:73], v[162:165], v[158:161]
	v_mfma_f32_16x16x32_bf16 v[154:157], v[82:85], v[162:165], v[154:157]
	v_mfma_f32_16x16x32_bf16 v[142:145], v[70:73], v[170:173], v[142:145]
	v_mfma_f32_16x16x32_bf16 v[138:141], v[82:85], v[170:173], v[138:141]
	v_mfma_f32_16x16x32_bf16 v[126:129], v[70:73], v[178:181], v[126:129]
	v_mfma_f32_16x16x32_bf16 v[122:125], v[82:85], v[178:181], v[122:125]
	v_mfma_f32_16x16x32_bf16 v[110:113], v[70:73], v[212:215], v[110:113]
	v_mfma_f32_16x16x32_bf16 v[98:101], v[82:85], v[212:215], v[98:101]
	v_mfma_f32_16x16x32_bf16 v[158:161], v[74:77], v[166:169], v[158:161]
	v_mfma_f32_16x16x32_bf16 v[154:157], v[86:89], v[166:169], v[154:157]
	v_mfma_f32_16x16x32_bf16 v[142:145], v[74:77], v[174:177], v[142:145]
	v_mfma_f32_16x16x32_bf16 v[138:141], v[86:89], v[174:177], v[138:141]
	v_mfma_f32_16x16x32_bf16 v[126:129], v[74:77], v[182:185], v[126:129]
	v_mfma_f32_16x16x32_bf16 v[122:125], v[86:89], v[182:185], v[122:125]
	v_mfma_f32_16x16x32_bf16 v[110:113], v[74:77], v[216:219], v[110:113]
	v_mfma_f32_16x16x32_bf16 v[98:101], v[86:89], v[216:219], v[98:101]
	s_setprio 0
	s_setprio 1
	v_mfma_f32_16x16x32_bf16 v[150:153], v[90:93], v[162:165], v[150:153]
	v_mfma_f32_16x16x32_bf16 v[146:149], v[102:105], v[162:165], v[146:149]
	v_mfma_f32_16x16x32_bf16 v[134:137], v[90:93], v[170:173], v[134:137]
	v_mfma_f32_16x16x32_bf16 v[130:133], v[102:105], v[170:173], v[130:133]
	v_mfma_f32_16x16x32_bf16 v[118:121], v[90:93], v[178:181], v[118:121]
	v_mfma_f32_16x16x32_bf16 v[114:117], v[102:105], v[178:181], v[114:117]
	v_mfma_f32_16x16x32_bf16 v[78:81], v[90:93], v[212:215], v[78:81]
	v_mfma_f32_16x16x32_bf16 v[66:69], v[102:105], v[212:215], v[66:69]
	v_mfma_f32_16x16x32_bf16 v[150:153], v[94:97], v[166:169], v[150:153]
	v_mfma_f32_16x16x32_bf16 v[146:149], v[106:109], v[166:169], v[146:149]
	v_mfma_f32_16x16x32_bf16 v[134:137], v[94:97], v[174:177], v[134:137]
	v_mfma_f32_16x16x32_bf16 v[130:133], v[106:109], v[174:177], v[130:133]
	v_mfma_f32_16x16x32_bf16 v[118:121], v[94:97], v[182:185], v[118:121]
	v_mfma_f32_16x16x32_bf16 v[114:117], v[106:109], v[182:185], v[114:117]
	v_mfma_f32_16x16x32_bf16 v[78:81], v[94:97], v[216:219], v[78:81]
	v_mfma_f32_16x16x32_bf16 v[66:69], v[106:109], v[216:219], v[66:69]
	s_setprio 0
	s_barrier
	s_add_i32 s75, s75, s6
	v_lshl_add_u64 v[220:221], s[44:45], 0, v[200:201]
	s_mov_b32 m0, s75
	ds_read_b128 v[162:165], v187 offset:16384
	ds_read_b128 v[166:169], v187 offset:17408
	ds_read_b128 v[170:173], v187 offset:18432
	ds_read_b128 v[174:177], v187 offset:19456
	ds_read_b128 v[178:181], v187 offset:20480
	ds_read_b128 v[182:185], v187 offset:21504
	ds_read_b128 v[212:215], v187 offset:22528
	ds_read_b128 v[216:219], v187 offset:23552
	global_load_lds_dwordx4 v[220:221], off
	s_add_i32 m0, s75, 0x2000
	s_add_u32 s78, s44, 0x40000
	v_lshl_add_u64 v[224:225], s[44:45], 0, v[196:197]
	s_addc_u32 s79, s45, 0
	s_add_i32 s75, s80, s6
	global_load_lds_dwordx4 v[224:225], off
	v_lshl_add_u64 v[226:227], s[78:79], 0, v[200:201]
	s_mov_b32 m0, s75
	v_lshl_add_u64 v[228:229], s[46:47], 0, v[198:199]
	global_load_lds_dwordx4 v[226:227], off
	v_lshl_add_u64 v[226:227], s[78:79], 0, v[196:197]
	s_add_i32 m0, s75, 0x2000
	s_nop 0
	global_load_lds_dwordx4 v[226:227], off
	v_lshl_add_u64 v[226:227], s[46:47], 0, v[202:203]
	s_mov_b32 m0, s41
	s_nop 0
	global_load_lds_dwordx4 v[226:227], off
	s_mov_b32 m0, s51
	s_nop 0
	global_load_lds_dwordx4 v[228:229], off
	s_waitcnt vmcnt(8)
	s_waitcnt lgkmcnt(0)
	s_barrier
	s_setprio 1
	s_waitcnt lgkmcnt(0)
	v_mfma_f32_16x16x32_bf16 v[62:65], v[70:73], v[162:165], v[62:65]
	v_mfma_f32_16x16x32_bf16 v[58:61], v[82:85], v[162:165], v[58:61]
	v_mfma_f32_16x16x32_bf16 v[46:49], v[70:73], v[170:173], v[46:49]
	v_mfma_f32_16x16x32_bf16 v[42:45], v[82:85], v[170:173], v[42:45]
	v_mfma_f32_16x16x32_bf16 v[30:33], v[70:73], v[178:181], v[30:33]
	v_mfma_f32_16x16x32_bf16 v[26:29], v[82:85], v[178:181], v[26:29]
	v_mfma_f32_16x16x32_bf16 v[14:17], v[70:73], v[212:215], v[14:17]
	v_mfma_f32_16x16x32_bf16 v[10:13], v[82:85], v[212:215], v[10:13]
	v_mfma_f32_16x16x32_bf16 v[62:65], v[74:77], v[166:169], v[62:65]
	v_mfma_f32_16x16x32_bf16 v[58:61], v[86:89], v[166:169], v[58:61]
	v_mfma_f32_16x16x32_bf16 v[46:49], v[74:77], v[174:177], v[46:49]
	v_mfma_f32_16x16x32_bf16 v[42:45], v[86:89], v[174:177], v[42:45]
	v_mfma_f32_16x16x32_bf16 v[30:33], v[74:77], v[182:185], v[30:33]
	v_mfma_f32_16x16x32_bf16 v[26:29], v[86:89], v[182:185], v[26:29]
	v_mfma_f32_16x16x32_bf16 v[14:17], v[74:77], v[216:219], v[14:17]
	v_mfma_f32_16x16x32_bf16 v[10:13], v[86:89], v[216:219], v[10:13]
	s_setprio 0
	s_setprio 1
	v_mfma_f32_16x16x32_bf16 v[54:57], v[90:93], v[162:165], v[54:57]
	v_mfma_f32_16x16x32_bf16 v[50:53], v[102:105], v[162:165], v[50:53]
	v_mfma_f32_16x16x32_bf16 v[38:41], v[90:93], v[170:173], v[38:41]
	v_mfma_f32_16x16x32_bf16 v[34:37], v[102:105], v[170:173], v[34:37]
	v_mfma_f32_16x16x32_bf16 v[22:25], v[90:93], v[178:181], v[22:25]
	v_mfma_f32_16x16x32_bf16 v[18:21], v[102:105], v[178:181], v[18:21]
	v_mfma_f32_16x16x32_bf16 v[6:9], v[90:93], v[212:215], v[6:9]
	v_mfma_f32_16x16x32_bf16 v[2:5], v[102:105], v[212:215], v[2:5]
	v_mfma_f32_16x16x32_bf16 v[54:57], v[94:97], v[166:169], v[54:57]
	v_mfma_f32_16x16x32_bf16 v[50:53], v[106:109], v[166:169], v[50:53]
	v_mfma_f32_16x16x32_bf16 v[38:41], v[94:97], v[174:177], v[38:41]
	v_mfma_f32_16x16x32_bf16 v[34:37], v[106:109], v[174:177], v[34:37]
	v_mfma_f32_16x16x32_bf16 v[22:25], v[94:97], v[182:185], v[22:25]
	v_mfma_f32_16x16x32_bf16 v[18:21], v[106:109], v[182:185], v[18:21]
	v_mfma_f32_16x16x32_bf16 v[6:9], v[94:97], v[216:219], v[6:9]
	v_mfma_f32_16x16x32_bf16 v[2:5], v[106:109], v[216:219], v[2:5]
	s_setprio 0
	s_barrier
	s_add_i32 s75, 0, 0x18000
	s_add_i32 s78, 0, 0x1c000
	v_add_u32_e32 v86, s75, v1
	v_add_u32_e32 v106, s78, v1
	ds_read_b128 v[70:73], v86
	ds_read_b128 v[74:77], v86 offset:1024
	ds_read_b128 v[82:85], v86 offset:2048
	ds_read_b128 v[86:89], v86 offset:3072
	ds_read_b128 v[90:93], v106
	ds_read_b128 v[94:97], v106 offset:1024
	ds_read_b128 v[102:105], v106 offset:2048
	ds_read_b128 v[106:109], v106 offset:3072
	s_add_u32 s46, s46, 0x40000
	s_addc_u32 s47, s47, 0
	s_mov_b32 m0, s56
	v_lshl_add_u64 v[230:231], s[46:47], 0, v[202:203]
	ds_read_b128 v[162:165], v187 offset:32768
	ds_read_b128 v[166:169], v187 offset:33792
	ds_read_b128 v[170:173], v187 offset:34816
	ds_read_b128 v[174:177], v187 offset:35840
	ds_read_b128 v[178:181], v187 offset:36864
	ds_read_b128 v[182:185], v187 offset:37888
	ds_read_b128 v[212:215], v187 offset:38912
	ds_read_b128 v[216:219], v187 offset:39936
	global_load_lds_dwordx4 v[230:231], off
	v_lshl_add_u64 v[230:231], s[46:47], 0, v[198:199]
	s_mov_b32 m0, s57
	s_nop 0
	global_load_lds_dwordx4 v[230:231], off
	s_waitcnt vmcnt(8)
	s_waitcnt lgkmcnt(0)
	s_barrier
	s_setprio 1
	s_waitcnt lgkmcnt(0)
	v_mfma_f32_16x16x32_bf16 v[158:161], v[70:73], v[162:165], v[158:161]
	v_mfma_f32_16x16x32_bf16 v[154:157], v[82:85], v[162:165], v[154:157]
	v_mfma_f32_16x16x32_bf16 v[142:145], v[70:73], v[170:173], v[142:145]
	v_mfma_f32_16x16x32_bf16 v[138:141], v[82:85], v[170:173], v[138:141]
	v_mfma_f32_16x16x32_bf16 v[126:129], v[70:73], v[178:181], v[126:129]
	v_mfma_f32_16x16x32_bf16 v[122:125], v[82:85], v[178:181], v[122:125]
	v_mfma_f32_16x16x32_bf16 v[110:113], v[70:73], v[212:215], v[110:113]
	v_mfma_f32_16x16x32_bf16 v[98:101], v[82:85], v[212:215], v[98:101]
	v_mfma_f32_16x16x32_bf16 v[158:161], v[74:77], v[166:169], v[158:161]
	v_mfma_f32_16x16x32_bf16 v[154:157], v[86:89], v[166:169], v[154:157]
	v_mfma_f32_16x16x32_bf16 v[142:145], v[74:77], v[174:177], v[142:145]
	v_mfma_f32_16x16x32_bf16 v[138:141], v[86:89], v[174:177], v[138:141]
	v_mfma_f32_16x16x32_bf16 v[126:129], v[74:77], v[182:185], v[126:129]
	v_mfma_f32_16x16x32_bf16 v[122:125], v[86:89], v[182:185], v[122:125]
	v_mfma_f32_16x16x32_bf16 v[110:113], v[74:77], v[216:219], v[110:113]
	v_mfma_f32_16x16x32_bf16 v[98:101], v[86:89], v[216:219], v[98:101]
	s_setprio 0
	s_setprio 1
	v_mfma_f32_16x16x32_bf16 v[150:153], v[90:93], v[162:165], v[150:153]
	v_mfma_f32_16x16x32_bf16 v[146:149], v[102:105], v[162:165], v[146:149]
	v_mfma_f32_16x16x32_bf16 v[134:137], v[90:93], v[170:173], v[134:137]
	v_mfma_f32_16x16x32_bf16 v[130:133], v[102:105], v[170:173], v[130:133]
	v_mfma_f32_16x16x32_bf16 v[118:121], v[90:93], v[178:181], v[118:121]
	v_mfma_f32_16x16x32_bf16 v[114:117], v[102:105], v[178:181], v[114:117]
	v_mfma_f32_16x16x32_bf16 v[78:81], v[90:93], v[212:215], v[78:81]
	v_mfma_f32_16x16x32_bf16 v[66:69], v[102:105], v[212:215], v[66:69]
	v_mfma_f32_16x16x32_bf16 v[150:153], v[94:97], v[166:169], v[150:153]
	v_mfma_f32_16x16x32_bf16 v[146:149], v[106:109], v[166:169], v[146:149]
	v_mfma_f32_16x16x32_bf16 v[134:137], v[94:97], v[174:177], v[134:137]
	v_mfma_f32_16x16x32_bf16 v[130:133], v[106:109], v[174:177], v[130:133]
	v_mfma_f32_16x16x32_bf16 v[118:121], v[94:97], v[182:185], v[118:121]
	v_mfma_f32_16x16x32_bf16 v[114:117], v[106:109], v[182:185], v[114:117]
	v_mfma_f32_16x16x32_bf16 v[78:81], v[94:97], v[216:219], v[78:81]
	v_mfma_f32_16x16x32_bf16 v[66:69], v[106:109], v[216:219], v[66:69]
	s_setprio 0
	s_barrier
	s_add_i32 s46, s75, s6
	v_lshl_add_u64 v[220:221], v[220:221], 0, s[66:67]
	s_mov_b32 m0, s46
	ds_read_b128 v[162:165], v187 offset:49152
	ds_read_b128 v[166:169], v187 offset:50176
	ds_read_b128 v[170:173], v187 offset:51200
	ds_read_b128 v[174:177], v187 offset:52224
	ds_read_b128 v[178:181], v187 offset:53248
	ds_read_b128 v[182:185], v187 offset:54272
	ds_read_b128 v[212:215], v187 offset:55296
	ds_read_b128 v[216:219], v187 offset:56320
	global_load_lds_dwordx4 v[220:221], off
	s_add_i32 m0, s46, 0x2000
	s_add_u32 s44, s44, 0x40080
	v_lshl_add_u64 v[220:221], v[224:225], 0, s[66:67]
	s_addc_u32 s45, s45, 0
	s_add_i32 s46, s78, s6
	global_load_lds_dwordx4 v[220:221], off
	v_lshl_add_u64 v[220:221], s[44:45], 0, v[200:201]
	s_mov_b32 m0, s46
	s_nop 0
	global_load_lds_dwordx4 v[220:221], off
	v_lshl_add_u64 v[220:221], s[44:45], 0, v[196:197]
	s_add_i32 m0, s46, 0x2000
	s_nop 0
	global_load_lds_dwordx4 v[220:221], off
	v_lshl_add_u64 v[220:221], v[226:227], 0, s[66:67]
	s_mov_b32 m0, s12
	s_nop 0
	global_load_lds_dwordx4 v[220:221], off
	v_lshl_add_u64 v[220:221], v[228:229], 0, s[66:67]
	s_mov_b32 m0, s13
	s_nop 0
	global_load_lds_dwordx4 v[220:221], off
	s_waitcnt vmcnt(8)
	s_waitcnt lgkmcnt(0)
	s_barrier
	s_setprio 1
	s_waitcnt lgkmcnt(0)
	v_mfma_f32_16x16x32_bf16 v[62:65], v[70:73], v[162:165], v[62:65]
	v_mfma_f32_16x16x32_bf16 v[58:61], v[82:85], v[162:165], v[58:61]
	v_mfma_f32_16x16x32_bf16 v[46:49], v[70:73], v[170:173], v[46:49]
	v_mfma_f32_16x16x32_bf16 v[42:45], v[82:85], v[170:173], v[42:45]
	v_mfma_f32_16x16x32_bf16 v[30:33], v[70:73], v[178:181], v[30:33]
	v_mfma_f32_16x16x32_bf16 v[26:29], v[82:85], v[178:181], v[26:29]
	v_mfma_f32_16x16x32_bf16 v[14:17], v[70:73], v[212:215], v[14:17]
	v_mfma_f32_16x16x32_bf16 v[10:13], v[82:85], v[212:215], v[10:13]
	v_mfma_f32_16x16x32_bf16 v[62:65], v[74:77], v[166:169], v[62:65]
	v_mfma_f32_16x16x32_bf16 v[58:61], v[86:89], v[166:169], v[58:61]
	v_mfma_f32_16x16x32_bf16 v[46:49], v[74:77], v[174:177], v[46:49]
	v_mfma_f32_16x16x32_bf16 v[42:45], v[86:89], v[174:177], v[42:45]
	v_mfma_f32_16x16x32_bf16 v[30:33], v[74:77], v[182:185], v[30:33]
	v_mfma_f32_16x16x32_bf16 v[26:29], v[86:89], v[182:185], v[26:29]
	v_mfma_f32_16x16x32_bf16 v[14:17], v[74:77], v[216:219], v[14:17]
	v_mfma_f32_16x16x32_bf16 v[10:13], v[86:89], v[216:219], v[10:13]
	s_setprio 0
	s_setprio 1
	v_mfma_f32_16x16x32_bf16 v[54:57], v[90:93], v[162:165], v[54:57]
	v_mfma_f32_16x16x32_bf16 v[50:53], v[102:105], v[162:165], v[50:53]
	v_mfma_f32_16x16x32_bf16 v[38:41], v[90:93], v[170:173], v[38:41]
	v_mfma_f32_16x16x32_bf16 v[34:37], v[102:105], v[170:173], v[34:37]
	v_mfma_f32_16x16x32_bf16 v[22:25], v[90:93], v[178:181], v[22:25]
	v_mfma_f32_16x16x32_bf16 v[18:21], v[102:105], v[178:181], v[18:21]
	v_mfma_f32_16x16x32_bf16 v[6:9], v[90:93], v[212:215], v[6:9]
	v_mfma_f32_16x16x32_bf16 v[2:5], v[102:105], v[212:215], v[2:5]
	v_mfma_f32_16x16x32_bf16 v[54:57], v[94:97], v[166:169], v[54:57]
	v_mfma_f32_16x16x32_bf16 v[50:53], v[106:109], v[166:169], v[50:53]
	v_mfma_f32_16x16x32_bf16 v[38:41], v[94:97], v[174:177], v[38:41]
	v_mfma_f32_16x16x32_bf16 v[34:37], v[106:109], v[174:177], v[34:37]
	v_mfma_f32_16x16x32_bf16 v[22:25], v[94:97], v[182:185], v[22:25]
	v_mfma_f32_16x16x32_bf16 v[18:21], v[106:109], v[182:185], v[18:21]
	v_mfma_f32_16x16x32_bf16 v[6:9], v[94:97], v[216:219], v[6:9]
	v_mfma_f32_16x16x32_bf16 v[2:5], v[106:109], v[216:219], v[2:5]
	s_setprio 0
	s_add_i32 s74, s74, 2
	s_add_u32 s72, s72, 0x100
	s_addc_u32 s73, s73, 0
	s_add_u32 s0, s0, 0x100
	s_addc_u32 s1, s1, 0
	s_add_u32 s44, s0, 0xfffc0080
	s_addc_u32 s45, s1, -1
	s_add_i32 s75, 0, 0x10000
	s_cmp_eq_u32 s74, 12
	s_cselect_b32 s47, s25, s45
	s_cselect_b32 s46, s43, s44
	s_cselect_b32 s45, s27, s73
	s_cselect_b32 s44, s53, s72
	s_add_i32 s80, 0, 0x14000
	s_waitcnt lgkmcnt(0)
	v_add_u32_e32 v86, s75, v1
	v_add_u32_e32 v106, s80, v1
	s_cmp_gt_u32 s74, 13
	s_barrier
	s_cbranch_scc0 .LBB0_577
	s_and_b64 vcc, exec, s[20:21]
	s_cbranch_vccz .LBB0_580
	s_barrier

.LBB0_804:
	s_add_i32 s40, s36, 2
	s_add_u32 s41, s30, 0x80
	s_addc_u32 s37, s31, 0
	s_add_i32 s45, 0, 0x10000
	s_cmp_eq_u32 s75, s36
	s_cselect_b32 s37, s27, s37
	s_cselect_b32 s36, s26, s41
	s_cselect_b32 s47, s29, s43
	s_cselect_b32 s46, s28, s3
	s_add_i32 s41, 0, 0x14000
	v_add_u32_e32 v78, s45, v1
	v_add_u32_e32 v102, s41, v1
	ds_read_b128 v[66:69], v78
	ds_read_b128 v[70:73], v78 offset:1024
	ds_read_b128 v[74:77], v78 offset:2048
	ds_read_b128 v[78:81], v78 offset:3072
	ds_read_b128 v[86:89], v102
	ds_read_b128 v[90:93], v102 offset:1024
	ds_read_b128 v[98:101], v102 offset:2048
	ds_read_b128 v[102:105], v102 offset:3072
	v_lshl_add_u64 v[184:185], s[30:31], 0, v[170:171]
	s_add_i32 m0, s87, 0xc000
	ds_read_b128 v[176:179], v187
	ds_read_b128 v[180:183], v187 offset:1024
	ds_read_b128 v[196:199], v187 offset:2048
	ds_read_b128 v[200:203], v187 offset:3072
	ds_read_b128 v[204:207], v187 offset:4096
	ds_read_b128 v[208:211], v187 offset:5120
	ds_read_b128 v[212:215], v187 offset:6144
	ds_read_b128 v[224:227], v187 offset:7168
	global_load_lds_dwordx4 v[184:185], off
	v_lshl_add_u64 v[184:185], s[30:31], 0, v[168:169]
	s_add_i32 m0, s87, 0xe000
	s_nop 0
	global_load_lds_dwordx4 v[184:185], off
	s_waitcnt vmcnt(8)
	s_waitcnt lgkmcnt(0)
	s_barrier
	s_setprio 1
	s_waitcnt lgkmcnt(0)
	v_mfma_f32_16x16x32_bf16 v[158:161], v[66:69], v[176:179], v[158:161]
	v_mfma_f32_16x16x32_bf16 v[154:157], v[74:77], v[176:179], v[154:157]
	v_mfma_f32_16x16x32_bf16 v[142:145], v[66:69], v[196:199], v[142:145]
	v_mfma_f32_16x16x32_bf16 v[138:141], v[74:77], v[196:199], v[138:141]
	v_mfma_f32_16x16x32_bf16 v[126:129], v[66:69], v[204:207], v[126:129]
	v_mfma_f32_16x16x32_bf16 v[122:125], v[74:77], v[204:207], v[122:125]
	v_mfma_f32_16x16x32_bf16 v[110:113], v[66:69], v[212:215], v[110:113]
	v_mfma_f32_16x16x32_bf16 v[106:109], v[74:77], v[212:215], v[106:109]
	v_mfma_f32_16x16x32_bf16 v[158:161], v[70:73], v[180:183], v[158:161]
	v_mfma_f32_16x16x32_bf16 v[154:157], v[78:81], v[180:183], v[154:157]
	v_mfma_f32_16x16x32_bf16 v[142:145], v[70:73], v[200:203], v[142:145]
	v_mfma_f32_16x16x32_bf16 v[138:141], v[78:81], v[200:203], v[138:141]
	v_mfma_f32_16x16x32_bf16 v[126:129], v[70:73], v[208:211], v[126:129]
	v_mfma_f32_16x16x32_bf16 v[122:125], v[78:81], v[208:211], v[122:125]
	v_mfma_f32_16x16x32_bf16 v[110:113], v[70:73], v[224:227], v[110:113]
	v_mfma_f32_16x16x32_bf16 v[106:109], v[78:81], v[224:227], v[106:109]
	s_setprio 0
	s_setprio 1
	v_mfma_f32_16x16x32_bf16 v[150:153], v[86:89], v[176:179], v[150:153]
	v_mfma_f32_16x16x32_bf16 v[146:149], v[98:101], v[176:179], v[146:149]
	v_mfma_f32_16x16x32_bf16 v[134:137], v[86:89], v[196:199], v[134:137]
	v_mfma_f32_16x16x32_bf16 v[130:133], v[98:101], v[196:199], v[130:133]
	v_mfma_f32_16x16x32_bf16 v[118:121], v[86:89], v[204:207], v[118:121]
	v_mfma_f32_16x16x32_bf16 v[114:117], v[98:101], v[204:207], v[114:117]
	v_mfma_f32_16x16x32_bf16 v[94:97], v[86:89], v[212:215], v[94:97]
	v_mfma_f32_16x16x32_bf16 v[82:85], v[98:101], v[212:215], v[82:85]
	v_mfma_f32_16x16x32_bf16 v[150:153], v[90:93], v[180:183], v[150:153]
	v_mfma_f32_16x16x32_bf16 v[146:149], v[102:105], v[180:183], v[146:149]
	v_mfma_f32_16x16x32_bf16 v[134:137], v[90:93], v[200:203], v[134:137]
	v_mfma_f32_16x16x32_bf16 v[130:133], v[102:105], v[200:203], v[130:133]
	v_mfma_f32_16x16x32_bf16 v[118:121], v[90:93], v[208:211], v[118:121]
	v_mfma_f32_16x16x32_bf16 v[114:117], v[102:105], v[208:211], v[114:117]
	v_mfma_f32_16x16x32_bf16 v[94:97], v[90:93], v[224:227], v[94:97]
	v_mfma_f32_16x16x32_bf16 v[82:85], v[102:105], v[224:227], v[82:85]
	s_setprio 0
	s_barrier
	s_add_i32 s45, s45, s63
	v_lshl_add_u64 v[184:185], s[46:47], 0, v[164:165]
	s_mov_b32 m0, s45
	ds_read_b128 v[176:179], v187 offset:16384
	ds_read_b128 v[180:183], v187 offset:17408
	ds_read_b128 v[196:199], v187 offset:18432
	ds_read_b128 v[200:203], v187 offset:19456
	ds_read_b128 v[204:207], v187 offset:20480
	ds_read_b128 v[208:211], v187 offset:21504
	ds_read_b128 v[212:215], v187 offset:22528
	ds_read_b128 v[224:227], v187 offset:23552
	global_load_lds_dwordx4 v[184:185], off
	s_add_i32 m0, s45, 0x2000
	v_lshl_add_u64 v[216:217], s[46:47], 0, v[166:167]
	s_add_u32 s46, s46, s16
	s_addc_u32 s47, s47, 0
	s_add_i32 s41, s41, s63
	global_load_lds_dwordx4 v[216:217], off
	v_lshl_add_u64 v[220:221], s[46:47], 0, v[164:165]
	s_mov_b32 m0, s41
	v_lshl_add_u64 v[228:229], s[46:47], 0, v[166:167]
	global_load_lds_dwordx4 v[220:221], off
	s_add_i32 m0, s41, 0x2000
	v_lshl_add_u64 v[230:231], s[36:37], 0, v[164:165]
	global_load_lds_dwordx4 v[228:229], off
	s_mov_b32 m0, s87
	v_lshl_add_u64 v[232:233], s[36:37], 0, v[166:167]
	global_load_lds_dwordx4 v[230:231], off
	s_mov_b32 m0, s82
	s_nop 0
	global_load_lds_dwordx4 v[232:233], off
	s_waitcnt vmcnt(8)
	s_waitcnt lgkmcnt(0)
	s_barrier
	s_setprio 1
	s_waitcnt lgkmcnt(0)
	v_mfma_f32_16x16x32_bf16 v[62:65], v[66:69], v[176:179], v[62:65]
	v_mfma_f32_16x16x32_bf16 v[58:61], v[74:77], v[176:179], v[58:61]
	v_mfma_f32_16x16x32_bf16 v[46:49], v[66:69], v[196:199], v[46:49]
	v_mfma_f32_16x16x32_bf16 v[42:45], v[74:77], v[196:199], v[42:45]
	v_mfma_f32_16x16x32_bf16 v[30:33], v[66:69], v[204:207], v[30:33]
	v_mfma_f32_16x16x32_bf16 v[26:29], v[74:77], v[204:207], v[26:29]
	v_mfma_f32_16x16x32_bf16 v[14:17], v[66:69], v[212:215], v[14:17]
	v_mfma_f32_16x16x32_bf16 v[10:13], v[74:77], v[212:215], v[10:13]
	v_mfma_f32_16x16x32_bf16 v[62:65], v[70:73], v[180:183], v[62:65]
	v_mfma_f32_16x16x32_bf16 v[58:61], v[78:81], v[180:183], v[58:61]
	v_mfma_f32_16x16x32_bf16 v[46:49], v[70:73], v[200:203], v[46:49]
	v_mfma_f32_16x16x32_bf16 v[42:45], v[78:81], v[200:203], v[42:45]
	v_mfma_f32_16x16x32_bf16 v[30:33], v[70:73], v[208:211], v[30:33]
	v_mfma_f32_16x16x32_bf16 v[26:29], v[78:81], v[208:211], v[26:29]
	v_mfma_f32_16x16x32_bf16 v[14:17], v[70:73], v[224:227], v[14:17]
	v_mfma_f32_16x16x32_bf16 v[10:13], v[78:81], v[224:227], v[10:13]
	s_setprio 0
	s_setprio 1
	v_mfma_f32_16x16x32_bf16 v[54:57], v[86:89], v[176:179], v[54:57]
	v_mfma_f32_16x16x32_bf16 v[50:53], v[98:101], v[176:179], v[50:53]
	v_mfma_f32_16x16x32_bf16 v[38:41], v[86:89], v[196:199], v[38:41]
	v_mfma_f32_16x16x32_bf16 v[34:37], v[98:101], v[196:199], v[34:37]
	v_mfma_f32_16x16x32_bf16 v[22:25], v[86:89], v[204:207], v[22:25]
	v_mfma_f32_16x16x32_bf16 v[18:21], v[98:101], v[204:207], v[18:21]
	v_mfma_f32_16x16x32_bf16 v[6:9], v[86:89], v[212:215], v[6:9]
	v_mfma_f32_16x16x32_bf16 v[2:5], v[98:101], v[212:215], v[2:5]
	v_mfma_f32_16x16x32_bf16 v[54:57], v[90:93], v[180:183], v[54:57]
	v_mfma_f32_16x16x32_bf16 v[50:53], v[102:105], v[180:183], v[50:53]
	v_mfma_f32_16x16x32_bf16 v[38:41], v[90:93], v[200:203], v[38:41]
	v_mfma_f32_16x16x32_bf16 v[34:37], v[102:105], v[200:203], v[34:37]
	v_mfma_f32_16x16x32_bf16 v[22:25], v[90:93], v[208:211], v[22:25]
	v_mfma_f32_16x16x32_bf16 v[18:21], v[102:105], v[208:211], v[18:21]
	v_mfma_f32_16x16x32_bf16 v[6:9], v[90:93], v[224:227], v[6:9]
	v_mfma_f32_16x16x32_bf16 v[2:5], v[102:105], v[224:227], v[2:5]
	s_setprio 0
	s_barrier
	s_add_i32 s41, 0, 0x18000
	s_add_i32 s45, 0, 0x1c000
	v_add_u32_e32 v78, s41, v1
	v_add_u32_e32 v102, s45, v1
	ds_read_b128 v[66:69], v78
	ds_read_b128 v[70:73], v78 offset:1024
	ds_read_b128 v[74:77], v78 offset:2048
	ds_read_b128 v[78:81], v78 offset:3072
	ds_read_b128 v[86:89], v102
	ds_read_b128 v[90:93], v102 offset:1024
	ds_read_b128 v[98:101], v102 offset:2048
	ds_read_b128 v[102:105], v102 offset:3072
	s_add_u32 s36, s36, s16
	s_addc_u32 s37, s37, 0
	s_mov_b32 m0, s83
	v_lshl_add_u64 v[234:235], s[36:37], 0, v[164:165]
	ds_read_b128 v[176:179], v187 offset:32768
	ds_read_b128 v[180:183], v187 offset:33792
	ds_read_b128 v[196:199], v187 offset:34816
	ds_read_b128 v[200:203], v187 offset:35840
	ds_read_b128 v[204:207], v187 offset:36864
	ds_read_b128 v[208:211], v187 offset:37888
	ds_read_b128 v[212:215], v187 offset:38912
	ds_read_b128 v[224:227], v187 offset:39936
	global_load_lds_dwordx4 v[234:235], off
	v_lshl_add_u64 v[234:235], s[36:37], 0, v[166:167]
	s_mov_b32 m0, s84
	s_nop 0
	global_load_lds_dwordx4 v[234:235], off
	s_waitcnt vmcnt(8)
	s_waitcnt lgkmcnt(0)
	s_barrier
	s_setprio 1
	s_waitcnt lgkmcnt(0)
	v_mfma_f32_16x16x32_bf16 v[158:161], v[66:69], v[176:179], v[158:161]
	v_mfma_f32_16x16x32_bf16 v[154:157], v[74:77], v[176:179], v[154:157]
	v_mfma_f32_16x16x32_bf16 v[142:145], v[66:69], v[196:199], v[142:145]
	v_mfma_f32_16x16x32_bf16 v[138:141], v[74:77], v[196:199], v[138:141]
	v_mfma_f32_16x16x32_bf16 v[126:129], v[66:69], v[204:207], v[126:129]
	v_mfma_f32_16x16x32_bf16 v[122:125], v[74:77], v[204:207], v[122:125]
	v_mfma_f32_16x16x32_bf16 v[110:113], v[66:69], v[212:215], v[110:113]
	v_mfma_f32_16x16x32_bf16 v[106:109], v[74:77], v[212:215], v[106:109]
	v_mfma_f32_16x16x32_bf16 v[158:161], v[70:73], v[180:183], v[158:161]
	v_mfma_f32_16x16x32_bf16 v[154:157], v[78:81], v[180:183], v[154:157]
	v_mfma_f32_16x16x32_bf16 v[142:145], v[70:73], v[200:203], v[142:145]
	v_mfma_f32_16x16x32_bf16 v[138:141], v[78:81], v[200:203], v[138:141]
	v_mfma_f32_16x16x32_bf16 v[126:129], v[70:73], v[208:211], v[126:129]
	v_mfma_f32_16x16x32_bf16 v[122:125], v[78:81], v[208:211], v[122:125]
	v_mfma_f32_16x16x32_bf16 v[110:113], v[70:73], v[224:227], v[110:113]
	v_mfma_f32_16x16x32_bf16 v[106:109], v[78:81], v[224:227], v[106:109]
	s_setprio 0
	s_setprio 1
	v_mfma_f32_16x16x32_bf16 v[150:153], v[86:89], v[176:179], v[150:153]
	v_mfma_f32_16x16x32_bf16 v[146:149], v[98:101], v[176:179], v[146:149]
	v_mfma_f32_16x16x32_bf16 v[134:137], v[86:89], v[196:199], v[134:137]
	v_mfma_f32_16x16x32_bf16 v[130:133], v[98:101], v[196:199], v[130:133]
	v_mfma_f32_16x16x32_bf16 v[118:121], v[86:89], v[204:207], v[118:121]
	v_mfma_f32_16x16x32_bf16 v[114:117], v[98:101], v[204:207], v[114:117]
	v_mfma_f32_16x16x32_bf16 v[94:97], v[86:89], v[212:215], v[94:97]
	v_mfma_f32_16x16x32_bf16 v[82:85], v[98:101], v[212:215], v[82:85]
	v_mfma_f32_16x16x32_bf16 v[150:153], v[90:93], v[180:183], v[150:153]
	v_mfma_f32_16x16x32_bf16 v[146:149], v[102:105], v[180:183], v[146:149]
	v_mfma_f32_16x16x32_bf16 v[134:137], v[90:93], v[200:203], v[134:137]
	v_mfma_f32_16x16x32_bf16 v[130:133], v[102:105], v[200:203], v[130:133]
	v_mfma_f32_16x16x32_bf16 v[118:121], v[90:93], v[208:211], v[118:121]
	v_mfma_f32_16x16x32_bf16 v[114:117], v[102:105], v[208:211], v[114:117]
	v_mfma_f32_16x16x32_bf16 v[94:97], v[90:93], v[224:227], v[94:97]
	v_mfma_f32_16x16x32_bf16 v[82:85], v[102:105], v[224:227], v[82:85]
	s_setprio 0
	s_barrier
	s_add_i32 s36, s41, s63
	v_lshl_add_u64 v[184:185], v[184:185], 0, s[66:67]
	s_mov_b32 m0, s36
	ds_read_b128 v[176:179], v187 offset:49152
	ds_read_b128 v[180:183], v187 offset:50176
	ds_read_b128 v[196:199], v187 offset:51200
	ds_read_b128 v[200:203], v187 offset:52224
	ds_read_b128 v[204:207], v187 offset:53248
	ds_read_b128 v[208:211], v187 offset:54272
	ds_read_b128 v[212:215], v187 offset:55296
	ds_read_b128 v[224:227], v187 offset:56320
	global_load_lds_dwordx4 v[184:185], off
	v_lshl_add_u64 v[184:185], v[216:217], 0, s[66:67]
	s_add_i32 m0, s36, 0x2000
	s_add_i32 s36, s45, s63
	global_load_lds_dwordx4 v[184:185], off
	v_lshl_add_u64 v[184:185], v[220:221], 0, s[66:67]
	s_mov_b32 m0, s36
	s_nop 0
	global_load_lds_dwordx4 v[184:185], off
	v_lshl_add_u64 v[184:185], v[228:229], 0, s[66:67]
	s_add_i32 m0, s36, 0x2000
	s_nop 0
	global_load_lds_dwordx4 v[184:185], off
	v_lshl_add_u64 v[184:185], v[230:231], 0, s[66:67]
	s_mov_b32 m0, s89
	s_nop 0
	global_load_lds_dwordx4 v[184:185], off
	v_lshl_add_u64 v[184:185], v[232:233], 0, s[66:67]
	s_mov_b32 m0, s74
	s_nop 0
	global_load_lds_dwordx4 v[184:185], off
	s_waitcnt vmcnt(8)
	s_waitcnt lgkmcnt(0)
	s_barrier
	s_setprio 1
	s_waitcnt lgkmcnt(0)
	v_mfma_f32_16x16x32_bf16 v[62:65], v[66:69], v[176:179], v[62:65]
	v_mfma_f32_16x16x32_bf16 v[58:61], v[74:77], v[176:179], v[58:61]
	v_mfma_f32_16x16x32_bf16 v[46:49], v[66:69], v[196:199], v[46:49]
	v_mfma_f32_16x16x32_bf16 v[42:45], v[74:77], v[196:199], v[42:45]
	v_mfma_f32_16x16x32_bf16 v[30:33], v[66:69], v[204:207], v[30:33]
	v_mfma_f32_16x16x32_bf16 v[26:29], v[74:77], v[204:207], v[26:29]
	v_mfma_f32_16x16x32_bf16 v[14:17], v[66:69], v[212:215], v[14:17]
	v_mfma_f32_16x16x32_bf16 v[10:13], v[74:77], v[212:215], v[10:13]
	v_mfma_f32_16x16x32_bf16 v[62:65], v[70:73], v[180:183], v[62:65]
	v_mfma_f32_16x16x32_bf16 v[58:61], v[78:81], v[180:183], v[58:61]
	v_mfma_f32_16x16x32_bf16 v[46:49], v[70:73], v[200:203], v[46:49]
	v_mfma_f32_16x16x32_bf16 v[42:45], v[78:81], v[200:203], v[42:45]
	v_mfma_f32_16x16x32_bf16 v[30:33], v[70:73], v[208:211], v[30:33]
	v_mfma_f32_16x16x32_bf16 v[26:29], v[78:81], v[208:211], v[26:29]
	v_mfma_f32_16x16x32_bf16 v[14:17], v[70:73], v[224:227], v[14:17]
	v_mfma_f32_16x16x32_bf16 v[10:13], v[78:81], v[224:227], v[10:13]
	s_setprio 0
	s_setprio 1
	v_mfma_f32_16x16x32_bf16 v[54:57], v[86:89], v[176:179], v[54:57]
	v_mfma_f32_16x16x32_bf16 v[50:53], v[98:101], v[176:179], v[50:53]
	v_mfma_f32_16x16x32_bf16 v[38:41], v[86:89], v[196:199], v[38:41]
	v_mfma_f32_16x16x32_bf16 v[34:37], v[98:101], v[196:199], v[34:37]
	v_mfma_f32_16x16x32_bf16 v[22:25], v[86:89], v[204:207], v[22:25]
	v_mfma_f32_16x16x32_bf16 v[18:21], v[98:101], v[204:207], v[18:21]
	v_mfma_f32_16x16x32_bf16 v[6:9], v[86:89], v[212:215], v[6:9]
	v_mfma_f32_16x16x32_bf16 v[2:5], v[98:101], v[212:215], v[2:5]
	v_mfma_f32_16x16x32_bf16 v[54:57], v[90:93], v[180:183], v[54:57]
	v_mfma_f32_16x16x32_bf16 v[50:53], v[102:105], v[180:183], v[50:53]
	v_mfma_f32_16x16x32_bf16 v[38:41], v[90:93], v[200:203], v[38:41]
	v_mfma_f32_16x16x32_bf16 v[34:37], v[102:105], v[200:203], v[34:37]
	v_mfma_f32_16x16x32_bf16 v[22:25], v[90:93], v[208:211], v[22:25]
	v_mfma_f32_16x16x32_bf16 v[18:21], v[102:105], v[208:211], v[18:21]
	v_mfma_f32_16x16x32_bf16 v[6:9], v[90:93], v[224:227], v[6:9]
	v_mfma_f32_16x16x32_bf16 v[2:5], v[102:105], v[224:227], v[2:5]
	s_setprio 0
	s_add_u32 s3, s3, 0x100
	s_addc_u32 s43, s43, 0
	s_add_u32 s30, s30, 0x100
	s_addc_u32 s31, s31, 0
	s_cmp_ge_u32 s40, s86
	s_mov_b32 s36, s40
	s_barrier
	s_cbranch_scc0 .LBB0_804
	s_and_b64 vcc, exec, s[22:23]
	s_cbranch_vccz .LBB0_807
	s_barrier

.LBB0_944:
	s_ashr_i32 s23, s22, 31
	s_lshl_b64 s[26:27], s[22:23], 19
	s_add_u32 s26, s96, s26
	s_addc_u32 s27, s97, s27
	s_and_b64 s[28:29], s[0:1], exec
	s_cselect_b32 s23, s27, s41
	s_cselect_b32 s56, s26, s40
	s_ashr_i32 s25, s24, 31
	s_lshl_b64 s[28:29], s[24:25], 19
	s_add_u32 s28, s16, s28
	s_addc_u32 s29, s17, s29
	s_and_b64 s[42:43], s[0:1], exec
	s_cselect_b32 s25, s29, s39
	s_cselect_b32 s57, s28, s38
	s_add_u32 s61, s38, 0x100
	s_addc_u32 s63, s39, 0
	s_add_u32 s38, s40, 0x40080
	v_mov_b32_e32 v2, 0
	s_addc_u32 s39, s41, 0
	s_mov_b32 s68, -2
	v_mov_b32_e32 v3, v2
	v_mov_b64_e32 v[4:5], 0
	v_mov_b64_e32 v[6:7], 0
	v_mov_b64_e32 v[8:9], 0
	v_mov_b64_e32 v[10:11], 0
	v_mov_b64_e32 v[12:13], 0
	v_mov_b64_e32 v[14:15], 0
	v_mov_b64_e32 v[16:17], 0
	v_mov_b64_e32 v[18:19], 0
	v_mov_b64_e32 v[20:21], 0
	v_mov_b64_e32 v[22:23], 0
	v_mov_b64_e32 v[24:25], 0
	v_mov_b64_e32 v[26:27], 0
	v_mov_b64_e32 v[28:29], 0
	v_mov_b64_e32 v[30:31], 0
	v_mov_b64_e32 v[32:33], 0
	v_mov_b64_e32 v[34:35], 0
	v_mov_b64_e32 v[36:37], 0
	v_mov_b64_e32 v[38:39], 0
	v_mov_b64_e32 v[40:41], 0
	v_mov_b64_e32 v[42:43], 0
	v_mov_b64_e32 v[44:45], 0
	v_mov_b64_e32 v[46:47], 0
	v_mov_b64_e32 v[48:49], 0
	v_mov_b64_e32 v[50:51], 0
	v_mov_b64_e32 v[52:53], 0
	v_mov_b64_e32 v[54:55], 0
	v_mov_b64_e32 v[56:57], 0
	v_mov_b64_e32 v[58:59], 0
	v_mov_b64_e32 v[60:61], 0
	v_mov_b64_e32 v[62:63], 0
	v_mov_b64_e32 v[64:65], 0
	v_mov_b64_e32 v[66:67], 0
	v_mov_b64_e32 v[68:69], 0
	v_mov_b64_e32 v[70:71], 0
	v_mov_b64_e32 v[72:73], 0
	v_mov_b64_e32 v[74:75], 0
	v_mov_b64_e32 v[76:77], 0
	v_mov_b64_e32 v[78:79], 0
	v_mov_b64_e32 v[80:81], 0
	v_mov_b64_e32 v[82:83], 0
	v_mov_b64_e32 v[84:85], 0
	v_mov_b64_e32 v[86:87], 0
	v_mov_b64_e32 v[88:89], 0
	v_mov_b64_e32 v[90:91], 0
	v_mov_b64_e32 v[92:93], 0
	v_mov_b64_e32 v[94:95], 0
	v_mov_b64_e32 v[96:97], 0
	v_mov_b64_e32 v[98:99], 0
	v_mov_b64_e32 v[100:101], 0
	v_mov_b64_e32 v[102:103], 0
	v_mov_b64_e32 v[104:105], 0
	v_mov_b64_e32 v[106:107], 0
	v_mov_b64_e32 v[108:109], 0
	v_mov_b64_e32 v[118:119], 0
	v_mov_b64_e32 v[120:121], 0
	v_mov_b64_e32 v[130:131], 0
	v_mov_b64_e32 v[132:133], 0
	v_mov_b64_e32 v[150:151], 0
	v_mov_b64_e32 v[152:153], 0
	v_mov_b64_e32 v[154:155], 0
	v_mov_b64_e32 v[156:157], 0
	v_mov_b64_e32 v[158:159], 0
	v_mov_b64_e32 v[160:161], 0
	s_add_u32 s40, s38, 0xfffc0080
	s_addc_u32 s41, s39, -1
	s_add_i32 s69, 0, 0x10000
	s_cmp_eq_u32 s68, 12
	s_cselect_b32 s43, s23, s41
	s_cselect_b32 s42, s56, s40
	s_cselect_b32 s41, s25, s63
	s_cselect_b32 s40, s57, s61
	s_add_i32 s74, 0, 0x14000
	v_add_u32_e32 v126, s69, v1
	v_add_u32_e32 v146, s74, v1
.LBB0_945:
	ds_read_b128 v[110:113], v126
	ds_read_b128 v[114:117], v126 offset:1024
	ds_read_b128 v[122:125], v126 offset:2048
	ds_read_b128 v[126:129], v126 offset:3072
	ds_read_b128 v[134:137], v146
	ds_read_b128 v[138:141], v146 offset:1024
	ds_read_b128 v[142:145], v146 offset:2048
	ds_read_b128 v[146:149], v146 offset:3072
	v_lshl_add_u64 v[184:185], s[38:39], 0, v[172:173]
	s_add_i32 m0, s31, 0xc000
	ds_read_b128 v[180:183], v178
	ds_read_b128 v[196:199], v178 offset:1024
	ds_read_b128 v[200:203], v178 offset:2048
	ds_read_b128 v[204:207], v178 offset:3072
	ds_read_b128 v[208:211], v178 offset:4096
	ds_read_b128 v[212:215], v178 offset:5120
	ds_read_b128 v[216:219], v178 offset:6144
	ds_read_b128 v[224:227], v178 offset:7168
	global_load_lds_dwordx4 v[184:185], off
	v_lshl_add_u64 v[184:185], s[38:39], 0, v[170:171]
	s_add_i32 m0, s31, 0xe000
	s_nop 0
	global_load_lds_dwordx4 v[184:185], off
	s_waitcnt vmcnt(8)
	s_waitcnt lgkmcnt(0)
	s_barrier
	s_setprio 1
	s_waitcnt lgkmcnt(0)
	v_mfma_f32_16x16x32_bf16 v[158:161], v[110:113], v[180:183], v[158:161]
	v_mfma_f32_16x16x32_bf16 v[150:153], v[122:125], v[180:183], v[150:153]
	v_mfma_f32_16x16x32_bf16 v[118:121], v[110:113], v[200:203], v[118:121]
	v_mfma_f32_16x16x32_bf16 v[102:105], v[122:125], v[200:203], v[102:105]
	v_mfma_f32_16x16x32_bf16 v[94:97], v[110:113], v[208:211], v[94:97]
	v_mfma_f32_16x16x32_bf16 v[86:89], v[122:125], v[208:211], v[86:89]
	v_mfma_f32_16x16x32_bf16 v[78:81], v[110:113], v[216:219], v[78:81]
	v_mfma_f32_16x16x32_bf16 v[70:73], v[122:125], v[216:219], v[70:73]
	v_mfma_f32_16x16x32_bf16 v[158:161], v[114:117], v[196:199], v[158:161]
	v_mfma_f32_16x16x32_bf16 v[150:153], v[126:129], v[196:199], v[150:153]
	v_mfma_f32_16x16x32_bf16 v[118:121], v[114:117], v[204:207], v[118:121]
	v_mfma_f32_16x16x32_bf16 v[102:105], v[126:129], v[204:207], v[102:105]
	v_mfma_f32_16x16x32_bf16 v[94:97], v[114:117], v[212:215], v[94:97]
	v_mfma_f32_16x16x32_bf16 v[86:89], v[126:129], v[212:215], v[86:89]
	v_mfma_f32_16x16x32_bf16 v[78:81], v[114:117], v[224:227], v[78:81]
	v_mfma_f32_16x16x32_bf16 v[70:73], v[126:129], v[224:227], v[70:73]
	s_setprio 0
	s_setprio 1
	v_mfma_f32_16x16x32_bf16 v[154:157], v[134:137], v[180:183], v[154:157]
	v_mfma_f32_16x16x32_bf16 v[130:133], v[142:145], v[180:183], v[130:133]
	v_mfma_f32_16x16x32_bf16 v[106:109], v[134:137], v[200:203], v[106:109]
	v_mfma_f32_16x16x32_bf16 v[98:101], v[142:145], v[200:203], v[98:101]
	v_mfma_f32_16x16x32_bf16 v[90:93], v[134:137], v[208:211], v[90:93]
	v_mfma_f32_16x16x32_bf16 v[82:85], v[142:145], v[208:211], v[82:85]
	v_mfma_f32_16x16x32_bf16 v[74:77], v[134:137], v[216:219], v[74:77]
	v_mfma_f32_16x16x32_bf16 v[66:69], v[142:145], v[216:219], v[66:69]
	v_mfma_f32_16x16x32_bf16 v[154:157], v[138:141], v[196:199], v[154:157]
	v_mfma_f32_16x16x32_bf16 v[130:133], v[146:149], v[196:199], v[130:133]
	v_mfma_f32_16x16x32_bf16 v[106:109], v[138:141], v[204:207], v[106:109]
	v_mfma_f32_16x16x32_bf16 v[98:101], v[146:149], v[204:207], v[98:101]
	v_mfma_f32_16x16x32_bf16 v[90:93], v[138:141], v[212:215], v[90:93]
	v_mfma_f32_16x16x32_bf16 v[82:85], v[146:149], v[212:215], v[82:85]
	v_mfma_f32_16x16x32_bf16 v[74:77], v[138:141], v[224:227], v[74:77]
	v_mfma_f32_16x16x32_bf16 v[66:69], v[146:149], v[224:227], v[66:69]
	s_setprio 0
	s_barrier
	s_add_i32 s69, s69, s44
	v_lshl_add_u64 v[184:185], s[40:41], 0, v[166:167]
	s_mov_b32 m0, s69
	ds_read_b128 v[180:183], v178 offset:16384
	ds_read_b128 v[196:199], v178 offset:17408
	ds_read_b128 v[200:203], v178 offset:18432
	ds_read_b128 v[204:207], v178 offset:19456
	ds_read_b128 v[208:211], v178 offset:20480
	ds_read_b128 v[212:215], v178 offset:21504
	ds_read_b128 v[216:219], v178 offset:22528
	ds_read_b128 v[224:227], v178 offset:23552
	global_load_lds_dwordx4 v[184:185], off
	s_add_i32 m0, s69, 0x2000
	s_add_u32 s72, s40, 0x40000
	v_lshl_add_u64 v[220:221], s[40:41], 0, v[162:163]
	s_addc_u32 s73, s41, 0
	s_add_i32 s69, s74, s44
	global_load_lds_dwordx4 v[220:221], off
	v_lshl_add_u64 v[228:229], s[72:73], 0, v[166:167]
	s_mov_b32 m0, s69
	v_lshl_add_u64 v[230:231], s[42:43], 0, v[164:165]
	global_load_lds_dwordx4 v[228:229], off
	v_lshl_add_u64 v[228:229], s[72:73], 0, v[162:163]
	s_add_i32 m0, s69, 0x2000
	s_nop 0
	global_load_lds_dwordx4 v[228:229], off
	v_lshl_add_u64 v[228:229], s[42:43], 0, v[168:169]
	s_mov_b32 m0, s31
	s_nop 0
	global_load_lds_dwordx4 v[228:229], off
	s_mov_b32 m0, s37
	s_nop 0
	global_load_lds_dwordx4 v[230:231], off
	s_waitcnt vmcnt(8)
	s_waitcnt lgkmcnt(0)
	s_barrier
	s_setprio 1
	s_waitcnt lgkmcnt(0)
	v_mfma_f32_16x16x32_bf16 v[62:65], v[110:113], v[180:183], v[62:65]
	v_mfma_f32_16x16x32_bf16 v[54:57], v[122:125], v[180:183], v[54:57]
	v_mfma_f32_16x16x32_bf16 v[46:49], v[110:113], v[200:203], v[46:49]
	v_mfma_f32_16x16x32_bf16 v[38:41], v[122:125], v[200:203], v[38:41]
	v_mfma_f32_16x16x32_bf16 v[30:33], v[110:113], v[208:211], v[30:33]
	v_mfma_f32_16x16x32_bf16 v[22:25], v[122:125], v[208:211], v[22:25]
	v_mfma_f32_16x16x32_bf16 v[14:17], v[110:113], v[216:219], v[14:17]
	v_mfma_f32_16x16x32_bf16 v[6:9], v[122:125], v[216:219], v[6:9]
	v_mfma_f32_16x16x32_bf16 v[62:65], v[114:117], v[196:199], v[62:65]
	v_mfma_f32_16x16x32_bf16 v[54:57], v[126:129], v[196:199], v[54:57]
	v_mfma_f32_16x16x32_bf16 v[46:49], v[114:117], v[204:207], v[46:49]
	v_mfma_f32_16x16x32_bf16 v[38:41], v[126:129], v[204:207], v[38:41]
	v_mfma_f32_16x16x32_bf16 v[30:33], v[114:117], v[212:215], v[30:33]
	v_mfma_f32_16x16x32_bf16 v[22:25], v[126:129], v[212:215], v[22:25]
	v_mfma_f32_16x16x32_bf16 v[14:17], v[114:117], v[224:227], v[14:17]
	v_mfma_f32_16x16x32_bf16 v[6:9], v[126:129], v[224:227], v[6:9]
	s_setprio 0
	s_setprio 1
	v_mfma_f32_16x16x32_bf16 v[58:61], v[134:137], v[180:183], v[58:61]
	v_mfma_f32_16x16x32_bf16 v[50:53], v[142:145], v[180:183], v[50:53]
	v_mfma_f32_16x16x32_bf16 v[42:45], v[134:137], v[200:203], v[42:45]
	v_mfma_f32_16x16x32_bf16 v[34:37], v[142:145], v[200:203], v[34:37]
	v_mfma_f32_16x16x32_bf16 v[26:29], v[134:137], v[208:211], v[26:29]
	v_mfma_f32_16x16x32_bf16 v[18:21], v[142:145], v[208:211], v[18:21]
	v_mfma_f32_16x16x32_bf16 v[10:13], v[134:137], v[216:219], v[10:13]
	v_mfma_f32_16x16x32_bf16 v[2:5], v[142:145], v[216:219], v[2:5]
	v_mfma_f32_16x16x32_bf16 v[58:61], v[138:141], v[196:199], v[58:61]
	v_mfma_f32_16x16x32_bf16 v[50:53], v[146:149], v[196:199], v[50:53]
	v_mfma_f32_16x16x32_bf16 v[42:45], v[138:141], v[204:207], v[42:45]
	v_mfma_f32_16x16x32_bf16 v[34:37], v[146:149], v[204:207], v[34:37]
	v_mfma_f32_16x16x32_bf16 v[26:29], v[138:141], v[212:215], v[26:29]
	v_mfma_f32_16x16x32_bf16 v[18:21], v[146:149], v[212:215], v[18:21]
	v_mfma_f32_16x16x32_bf16 v[10:13], v[138:141], v[224:227], v[10:13]
	v_mfma_f32_16x16x32_bf16 v[2:5], v[146:149], v[224:227], v[2:5]
	s_setprio 0
	s_barrier
	s_add_i32 s69, 0, 0x18000
	s_add_i32 s72, 0, 0x1c000
	v_add_u32_e32 v126, s69, v1
	v_add_u32_e32 v146, s72, v1
	ds_read_b128 v[110:113], v126
	ds_read_b128 v[114:117], v126 offset:1024
	ds_read_b128 v[122:125], v126 offset:2048
	ds_read_b128 v[126:129], v126 offset:3072
	ds_read_b128 v[134:137], v146
	ds_read_b128 v[138:141], v146 offset:1024
	ds_read_b128 v[142:145], v146 offset:2048
	ds_read_b128 v[146:149], v146 offset:3072
	s_add_u32 s42, s42, 0x40000
	s_addc_u32 s43, s43, 0
	s_mov_b32 m0, s47
	v_lshl_add_u64 v[232:233], s[42:43], 0, v[168:169]
	ds_read_b128 v[180:183], v178 offset:32768
	ds_read_b128 v[196:199], v178 offset:33792
	ds_read_b128 v[200:203], v178 offset:34816
	ds_read_b128 v[204:207], v178 offset:35840
	ds_read_b128 v[208:211], v178 offset:36864
	ds_read_b128 v[212:215], v178 offset:37888
	ds_read_b128 v[216:219], v178 offset:38912
	ds_read_b128 v[224:227], v178 offset:39936
	global_load_lds_dwordx4 v[232:233], off
	v_lshl_add_u64 v[232:233], s[42:43], 0, v[164:165]
	s_mov_b32 m0, s48
	s_nop 0
	global_load_lds_dwordx4 v[232:233], off
	s_waitcnt vmcnt(8)
	s_waitcnt lgkmcnt(0)
	s_barrier
	s_setprio 1
	s_waitcnt lgkmcnt(0)
	v_mfma_f32_16x16x32_bf16 v[158:161], v[110:113], v[180:183], v[158:161]
	v_mfma_f32_16x16x32_bf16 v[150:153], v[122:125], v[180:183], v[150:153]
	v_mfma_f32_16x16x32_bf16 v[118:121], v[110:113], v[200:203], v[118:121]
	v_mfma_f32_16x16x32_bf16 v[102:105], v[122:125], v[200:203], v[102:105]
	v_mfma_f32_16x16x32_bf16 v[94:97], v[110:113], v[208:211], v[94:97]
	v_mfma_f32_16x16x32_bf16 v[86:89], v[122:125], v[208:211], v[86:89]
	v_mfma_f32_16x16x32_bf16 v[78:81], v[110:113], v[216:219], v[78:81]
	v_mfma_f32_16x16x32_bf16 v[70:73], v[122:125], v[216:219], v[70:73]
	v_mfma_f32_16x16x32_bf16 v[158:161], v[114:117], v[196:199], v[158:161]
	v_mfma_f32_16x16x32_bf16 v[150:153], v[126:129], v[196:199], v[150:153]
	v_mfma_f32_16x16x32_bf16 v[118:121], v[114:117], v[204:207], v[118:121]
	v_mfma_f32_16x16x32_bf16 v[102:105], v[126:129], v[204:207], v[102:105]
	v_mfma_f32_16x16x32_bf16 v[94:97], v[114:117], v[212:215], v[94:97]
	v_mfma_f32_16x16x32_bf16 v[86:89], v[126:129], v[212:215], v[86:89]
	v_mfma_f32_16x16x32_bf16 v[78:81], v[114:117], v[224:227], v[78:81]
	v_mfma_f32_16x16x32_bf16 v[70:73], v[126:129], v[224:227], v[70:73]
	s_setprio 0
	s_setprio 1
	v_mfma_f32_16x16x32_bf16 v[154:157], v[134:137], v[180:183], v[154:157]
	v_mfma_f32_16x16x32_bf16 v[130:133], v[142:145], v[180:183], v[130:133]
	v_mfma_f32_16x16x32_bf16 v[106:109], v[134:137], v[200:203], v[106:109]
	v_mfma_f32_16x16x32_bf16 v[98:101], v[142:145], v[200:203], v[98:101]
	v_mfma_f32_16x16x32_bf16 v[90:93], v[134:137], v[208:211], v[90:93]
	v_mfma_f32_16x16x32_bf16 v[82:85], v[142:145], v[208:211], v[82:85]
	v_mfma_f32_16x16x32_bf16 v[74:77], v[134:137], v[216:219], v[74:77]
	v_mfma_f32_16x16x32_bf16 v[66:69], v[142:145], v[216:219], v[66:69]
	v_mfma_f32_16x16x32_bf16 v[154:157], v[138:141], v[196:199], v[154:157]
	v_mfma_f32_16x16x32_bf16 v[130:133], v[146:149], v[196:199], v[130:133]
	v_mfma_f32_16x16x32_bf16 v[106:109], v[138:141], v[204:207], v[106:109]
	v_mfma_f32_16x16x32_bf16 v[98:101], v[146:149], v[204:207], v[98:101]
	v_mfma_f32_16x16x32_bf16 v[90:93], v[138:141], v[212:215], v[90:93]
	v_mfma_f32_16x16x32_bf16 v[82:85], v[146:149], v[212:215], v[82:85]
	v_mfma_f32_16x16x32_bf16 v[74:77], v[138:141], v[224:227], v[74:77]
	v_mfma_f32_16x16x32_bf16 v[66:69], v[146:149], v[224:227], v[66:69]
	s_setprio 0
	s_barrier
	s_add_i32 s42, s69, s44
	v_lshl_add_u64 v[184:185], v[184:185], 0, s[66:67]
	s_mov_b32 m0, s42
	ds_read_b128 v[180:183], v178 offset:49152
	ds_read_b128 v[196:199], v178 offset:50176
	ds_read_b128 v[200:203], v178 offset:51200
	ds_read_b128 v[204:207], v178 offset:52224
	ds_read_b128 v[208:211], v178 offset:53248
	ds_read_b128 v[212:215], v178 offset:54272
	ds_read_b128 v[216:219], v178 offset:55296
	ds_read_b128 v[224:227], v178 offset:56320
	global_load_lds_dwordx4 v[184:185], off
	s_add_i32 m0, s42, 0x2000
	s_add_u32 s40, s40, 0x40080
	v_lshl_add_u64 v[184:185], v[220:221], 0, s[66:67]
	s_addc_u32 s41, s41, 0
	s_add_i32 s42, s72, s44
	global_load_lds_dwordx4 v[184:185], off
	v_lshl_add_u64 v[184:185], s[40:41], 0, v[166:167]
	s_mov_b32 m0, s42
	s_nop 0
	global_load_lds_dwordx4 v[184:185], off
	v_lshl_add_u64 v[184:185], s[40:41], 0, v[162:163]
	s_add_i32 m0, s42, 0x2000
	s_nop 0
	global_load_lds_dwordx4 v[184:185], off
	v_lshl_add_u64 v[184:185], v[228:229], 0, s[66:67]
	s_mov_b32 m0, s50
	s_nop 0
	global_load_lds_dwordx4 v[184:185], off
	v_lshl_add_u64 v[184:185], v[230:231], 0, s[66:67]
	s_mov_b32 m0, s51
	s_nop 0
	global_load_lds_dwordx4 v[184:185], off
	s_waitcnt vmcnt(8)
	s_waitcnt lgkmcnt(0)
	s_barrier
	s_setprio 1
	s_waitcnt lgkmcnt(0)
	v_mfma_f32_16x16x32_bf16 v[62:65], v[110:113], v[180:183], v[62:65]
	v_mfma_f32_16x16x32_bf16 v[54:57], v[122:125], v[180:183], v[54:57]
	v_mfma_f32_16x16x32_bf16 v[46:49], v[110:113], v[200:203], v[46:49]
	v_mfma_f32_16x16x32_bf16 v[38:41], v[122:125], v[200:203], v[38:41]
	v_mfma_f32_16x16x32_bf16 v[30:33], v[110:113], v[208:211], v[30:33]
	v_mfma_f32_16x16x32_bf16 v[22:25], v[122:125], v[208:211], v[22:25]
	v_mfma_f32_16x16x32_bf16 v[14:17], v[110:113], v[216:219], v[14:17]
	v_mfma_f32_16x16x32_bf16 v[6:9], v[122:125], v[216:219], v[6:9]
	v_mfma_f32_16x16x32_bf16 v[62:65], v[114:117], v[196:199], v[62:65]
	v_mfma_f32_16x16x32_bf16 v[54:57], v[126:129], v[196:199], v[54:57]
	v_mfma_f32_16x16x32_bf16 v[46:49], v[114:117], v[204:207], v[46:49]
	v_mfma_f32_16x16x32_bf16 v[38:41], v[126:129], v[204:207], v[38:41]
	v_mfma_f32_16x16x32_bf16 v[30:33], v[114:117], v[212:215], v[30:33]
	v_mfma_f32_16x16x32_bf16 v[22:25], v[126:129], v[212:215], v[22:25]
	v_mfma_f32_16x16x32_bf16 v[14:17], v[114:117], v[224:227], v[14:17]
	v_mfma_f32_16x16x32_bf16 v[6:9], v[126:129], v[224:227], v[6:9]
	s_setprio 0
	s_setprio 1
	v_mfma_f32_16x16x32_bf16 v[58:61], v[134:137], v[180:183], v[58:61]
	v_mfma_f32_16x16x32_bf16 v[50:53], v[142:145], v[180:183], v[50:53]
	v_mfma_f32_16x16x32_bf16 v[42:45], v[134:137], v[200:203], v[42:45]
	v_mfma_f32_16x16x32_bf16 v[34:37], v[142:145], v[200:203], v[34:37]
	v_mfma_f32_16x16x32_bf16 v[26:29], v[134:137], v[208:211], v[26:29]
	v_mfma_f32_16x16x32_bf16 v[18:21], v[142:145], v[208:211], v[18:21]
	v_mfma_f32_16x16x32_bf16 v[10:13], v[134:137], v[216:219], v[10:13]
	v_mfma_f32_16x16x32_bf16 v[2:5], v[142:145], v[216:219], v[2:5]
	v_mfma_f32_16x16x32_bf16 v[58:61], v[138:141], v[196:199], v[58:61]
	v_mfma_f32_16x16x32_bf16 v[50:53], v[146:149], v[196:199], v[50:53]
	v_mfma_f32_16x16x32_bf16 v[42:45], v[138:141], v[204:207], v[42:45]
	v_mfma_f32_16x16x32_bf16 v[34:37], v[146:149], v[204:207], v[34:37]
	v_mfma_f32_16x16x32_bf16 v[26:29], v[138:141], v[212:215], v[26:29]
	v_mfma_f32_16x16x32_bf16 v[18:21], v[146:149], v[212:215], v[18:21]
	v_mfma_f32_16x16x32_bf16 v[10:13], v[138:141], v[224:227], v[10:13]
	v_mfma_f32_16x16x32_bf16 v[2:5], v[146:149], v[224:227], v[2:5]
	s_setprio 0
	s_add_i32 s68, s68, 2
	s_add_u32 s61, s61, 0x100
	s_addc_u32 s63, s63, 0
	s_add_u32 s38, s38, 0x100
	s_addc_u32 s39, s39, 0
	s_add_u32 s40, s38, 0xfffc0080
	s_addc_u32 s41, s39, -1
	s_add_i32 s69, 0, 0x10000
	s_cmp_eq_u32 s68, 12
	s_cselect_b32 s43, s23, s41
	s_cselect_b32 s42, s56, s40
	s_cselect_b32 s41, s25, s63
	s_cselect_b32 s40, s57, s61
	s_add_i32 s74, 0, 0x14000
	v_add_u32_e32 v126, s69, v1
	v_add_u32_e32 v146, s74, v1
	s_cmp_gt_u32 s68, 13
	s_barrier
	s_cbranch_scc0 .LBB0_945
	s_and_b64 vcc, exec, s[20:21]
	s_cbranch_vccz .LBB0_948
	s_barrier
